# P0 row loop: 32 dead v_readlane reloads per trip hoisted to one copy at the loop exit
# speedup vs baseline: 1.0004x; 1.0001x over previous
.LBB0_26:
	v_add_u32_e32 v18, 0xffffc000, v42
	v_cmp_gt_i32_e32 vcc, s25, v42
	v_mov_b32_e32 v29, s54
	v_mov_b32_e32 v32, s52
	v_cndmask_b32_e32 v19, 0, v43, vcc
	v_cndmask_b32_e32 v18, v18, v42, vcc
	s_waitcnt lgkmcnt(0)
	v_cndmask_b32_e32 v21, v72, v73, vcc
	v_cndmask_b32_e32 v20, v29, v32, vcc
	v_lshlrev_b64 v[18:19], 12, v[18:19]
	v_lshl_add_u64 v[18:19], v[20:21], 0, v[18:19]
	v_lshl_add_u64 v[18:19], v[18:19], 0, v[44:45]
	global_load_dwordx4 v[56:59], v[18:19], off
	global_load_dwordx4 v[60:63], v[18:19], off offset:1024
	global_load_dwordx4 v[34:37], v[18:19], off offset:3072
	global_load_dwordx4 v[38:41], v[18:19], off offset:2048
	s_waitcnt vmcnt(3)
	v_pk_mul_f32 v[18:19], v[58:59], v[58:59]
	v_pk_mul_f32 v[20:21], v[56:57], v[56:57]
	s_waitcnt vmcnt(2)
	v_pk_mul_f32 v[22:23], v[62:63], v[62:63]
	v_pk_mul_f32 v[24:25], v[60:61], v[60:61]
	v_pk_mov_b32 v[30:31], v[20:21], v[18:19] op_sel:[1,0]
	v_mov_b32_e32 v21, v19
	v_pk_mov_b32 v[18:19], v[24:25], v[22:23] op_sel:[1,0]
	v_mov_b32_e32 v25, v23
	s_waitcnt vmcnt(0)
	v_mul_f32_e32 v26, v39, v39
	v_mul_f32_e32 v28, v41, v41
	v_pk_add_f32 v[20:21], v[30:31], v[20:21]
	v_pk_add_f32 v[18:19], v[18:19], v[24:25]
	v_mul_f32_e32 v33, v34, v34
	v_mul_f32_e32 v54, v35, v35
	v_mul_f32_e32 v55, v36, v36
	v_mul_f32_e32 v64, v37, v37
	v_pk_fma_f32 v[22:23], v[38:39], v[38:39], v[26:27] op_sel_hi:[1,1,0]
	v_pk_fma_f32 v[26:27], v[40:41], v[40:41], v[28:29] op_sel_hi:[1,1,0]
	v_pk_add_f32 v[20:21], v[20:21], v[20:21] op_sel:[0,1] op_sel_hi:[1,0]
	v_pk_add_f32 v[18:19], v[18:19], v[18:19] op_sel:[0,1] op_sel_hi:[1,0]
	v_mov_b32_e32 v23, v55
	v_mov_b32_e32 v27, v64
	v_mov_b32_e32 v21, v33
	v_mov_b32_e32 v19, v54
	v_pk_add_f32 v[22:23], v[22:23], v[26:27]
	v_pk_add_f32 v[18:19], v[20:21], v[18:19]
	v_add_u32_e32 v20, s33, v42
	v_pk_add_f32 v[18:19], v[18:19], v[22:23]
	v_cmp_gt_i32_e64 s[4:5], s24, v20
	v_add_f32_e32 v18, v18, v19
	ds_bpermute_b32 v19, v66, v18
	v_cndmask_b32_e64 v20, v42, v20, s[4:5]
	v_add_u32_e32 v25, 0xffffc000, v20
	v_mov_b32_e32 v21, s55
	v_mov_b32_e32 v24, s53
	s_waitcnt lgkmcnt(0)
	v_add_f32_e32 v18, v18, v19
	ds_bpermute_b32 v19, v67, v18
	s_waitcnt lgkmcnt(0)
	v_add_f32_e32 v22, v18, v19
	ds_bpermute_b32 v23, v68, v22
	v_lshl_add_u64 v[18:19], s[74:75], 0, v[50:51]
	v_add_co_u32_e32 v54, vcc, s29, v18
	v_ashrrev_i32_e32 v18, 31, v20
	s_waitcnt lgkmcnt(0)
	v_add_f32_e32 v22, v22, v23
	ds_bpermute_b32 v23, v69, v22
	v_addc_co_u32_e32 v55, vcc, 0, v19, vcc
	v_cmp_gt_i32_e32 vcc, s25, v20
	s_waitcnt lgkmcnt(0)
	v_add_f32_e32 v22, v22, v23
	ds_bpermute_b32 v23, v70, v22
	v_cndmask_b32_e32 v19, 0, v18, vcc
	v_cndmask_b32_e32 v18, v25, v20, vcc
	v_cndmask_b32_e32 v21, v21, v24, vcc
	v_cndmask_b32_e32 v20, v29, v32, vcc
	s_waitcnt lgkmcnt(0)
	v_add_f32_e32 v22, v22, v23
	ds_bpermute_b32 v23, v71, v22
	v_lshlrev_b64 v[18:19], 12, v[18:19]
	v_lshl_add_u64 v[18:19], v[20:21], 0, v[18:19]
	v_lshl_add_u64 v[18:19], v[18:19], 0, v[44:45]
	s_waitcnt lgkmcnt(0)
	v_add_f32_e32 v20, v22, v23
	v_fmamk_f32 v20, v20, 0x3a800000, v74
	v_mul_f32_e32 v21, 0x4b800000, v20
	v_cmp_gt_f32_e32 vcc, s28, v20
	s_nop 1
	v_cndmask_b32_e32 v20, v20, v21, vcc
	v_rsq_f32_e32 v64, v20
	global_load_dwordx4 v[30:33], v[18:19], off
	global_load_dwordx4 v[26:29], v[18:19], off offset:1024
	global_load_dwordx4 v[22:25], v[18:19], off offset:2048
	s_nop 0
	global_load_dwordx4 v[18:21], v[18:19], off offset:3072
	v_mul_f32_e32 v65, 0x45800000, v64
	v_cndmask_b32_e32 v64, v64, v65, vcc
	v_pk_mul_f32 v[56:57], v[56:57], v[64:65] op_sel_hi:[1,0]
	v_pk_mul_f32 v[58:59], v[58:59], v[64:65] op_sel_hi:[1,0]
	v_pk_mul_f32 v[38:39], v[38:39], v[64:65] op_sel_hi:[1,0]
	v_pk_mul_f32 v[34:35], v[34:35], v[64:65] op_sel_hi:[1,0]
	v_pk_mul_f32 v[60:61], v[60:61], v[64:65] op_sel_hi:[1,0]
	v_pk_mul_f32 v[78:79], v[62:63], v[64:65] op_sel_hi:[1,0]
	v_pk_mul_f32 v[40:41], v[40:41], v[64:65] op_sel_hi:[1,0]
	v_pk_mul_f32 v[36:37], v[36:37], v[64:65] op_sel_hi:[1,0]
	v_pk_mul_f32 v[62:63], v[4:5], v[58:59]
	v_pk_mul_f32 v[64:65], v[2:3], v[56:57]
	v_pk_mul_f32 v[56:57], v[10:11], v[38:39]
	v_pk_mul_f32 v[38:39], v[14:15], v[34:35]
	v_cvt_pk_bf16_f32 v34, v64, v65
	v_cvt_pk_bf16_f32 v35, v62, v63
	v_pk_mul_f32 v[58:59], v[8:9], v[78:79]
	v_pk_mul_f32 v[60:61], v[6:7], v[60:61]
	global_store_dwordx2 v[54:55], v[34:35], off
	v_cvt_pk_bf16_f32 v34, v60, v61
	v_cvt_pk_bf16_f32 v35, v58, v59
	v_pk_mul_f32 v[40:41], v[12:13], v[40:41]
	global_store_dwordx2 v[54:55], v[34:35], off offset:512
	v_cvt_pk_bf16_f32 v34, v56, v57
	v_cvt_pk_bf16_f32 v35, v40, v41
	v_pk_mul_f32 v[36:37], v[16:17], v[36:37]
	global_store_dwordx2 v[54:55], v[34:35], off offset:1024
	v_cvt_pk_bf16_f32 v34, v38, v39
	v_cvt_pk_bf16_f32 v35, v36, v37
	ds_read_b128 v[78:81], v1
	ds_read_b128 v[82:85], v1 offset:1024
	ds_read_b128 v[86:89], v1 offset:2048
	ds_read_b128 v[90:93], v1 offset:3072
	ds_read_b128 v[94:97], v1 offset:4096
	ds_read_b128 v[98:101], v1 offset:5120
	ds_read_b128 v[102:105], v1 offset:6144
	ds_read_b128 v[106:109], v1 offset:7168
	s_waitcnt lgkmcnt(7)
	v_mul_f32_e32 v77, v65, v79
	v_mul_f32_e32 v79, v63, v81
	s_waitcnt lgkmcnt(6)
	v_mul_f32_e32 v81, v61, v83
	v_mul_f32_e32 v83, v59, v85
	v_fmac_f32_e32 v77, v64, v78
	v_fmac_f32_e32 v79, v62, v80
	s_waitcnt lgkmcnt(5)
	v_mul_f32_e32 v85, v57, v87
	v_mul_f32_e32 v87, v41, v89
	v_fmac_f32_e32 v81, v60, v82
	v_fmac_f32_e32 v83, v58, v84
	v_add_f32_e32 v77, v77, v79
	s_waitcnt lgkmcnt(4)
	v_mul_f32_e32 v89, v39, v91
	v_mul_f32_e32 v91, v37, v93
	v_fmac_f32_e32 v85, v56, v86
	v_fmac_f32_e32 v87, v40, v88
	v_add_f32_e32 v78, v81, v83
	v_add_f32_e32 v77, 0, v77
	v_fmac_f32_e32 v89, v38, v90
	v_fmac_f32_e32 v91, v36, v92
	v_add_f32_e32 v79, v85, v87
	v_add_f32_e32 v77, v77, v78
	s_waitcnt lgkmcnt(3)
	v_mul_f32_e32 v93, v65, v95
	v_mul_f32_e32 v95, v63, v97
	v_add_f32_e32 v80, v89, v91
	v_add_f32_e32 v77, v77, v79
	s_waitcnt lgkmcnt(2)
	v_mul_f32_e32 v97, v61, v99
	v_mul_f32_e32 v99, v59, v101
	v_fmac_f32_e32 v93, v64, v94
	v_fmac_f32_e32 v95, v62, v96
	v_add_f32_e32 v77, v77, v80
	v_fmac_f32_e32 v97, v60, v98
	v_fmac_f32_e32 v99, v58, v100
	ds_bpermute_b32 v78, v66, v77
	v_add_f32_e32 v79, v93, v95
	v_add_f32_e32 v80, v97, v99
	v_add_f32_e32 v79, 0, v79
	s_waitcnt lgkmcnt(2)
	v_mul_f32_e32 v101, v57, v103
	v_add_f32_e32 v79, v79, v80
	v_mul_f32_e32 v80, v41, v105
	v_fmac_f32_e32 v101, v56, v102
	v_fmac_f32_e32 v80, v40, v104
	v_add_f32_e32 v80, v101, v80
	s_waitcnt lgkmcnt(0)
	v_add_f32_e32 v77, v77, v78
	v_add_f32_e32 v79, v79, v80
	v_mul_f32_e32 v80, v39, v107
	v_mul_f32_e32 v81, v37, v109
	ds_bpermute_b32 v78, v67, v77
	v_fmac_f32_e32 v80, v38, v106
	v_fmac_f32_e32 v81, v36, v108
	v_add_f32_e32 v80, v80, v81
	v_add_f32_e32 v79, v79, v80
	ds_bpermute_b32 v80, v66, v79
	s_waitcnt lgkmcnt(1)
	v_add_f32_e32 v77, v77, v78
	ds_bpermute_b32 v78, v68, v77
	global_store_dwordx2 v[54:55], v[34:35], off offset:1536
	s_waitcnt lgkmcnt(1)
	v_add_f32_e32 v82, v79, v80
	ds_bpermute_b32 v83, v67, v82
	s_waitcnt lgkmcnt(1)
	v_add_f32_e32 v77, v77, v78
	ds_read_b128 v[78:81], v1 offset:8192
	ds_bpermute_b32 v86, v69, v77
	s_waitcnt lgkmcnt(2)
	v_add_f32_e32 v87, v82, v83
	ds_read_b128 v[82:85], v1 offset:9216
	s_waitcnt lgkmcnt(2)
	v_mul_f32_e32 v79, v65, v79
	v_fmac_f32_e32 v79, v64, v78
	v_mul_f32_e32 v78, v63, v81
	v_fmac_f32_e32 v78, v62, v80
	v_add_f32_e32 v78, v79, v78
	s_waitcnt lgkmcnt(0)
	v_mul_f32_e32 v83, v61, v83
	v_add_f32_e32 v89, 0, v78
	v_fmac_f32_e32 v83, v60, v82
	v_mul_f32_e32 v82, v59, v85
	ds_read_b128 v[78:81], v1 offset:10240
	v_fmac_f32_e32 v82, v58, v84
	v_add_f32_e32 v82, v83, v82
	v_add_f32_e32 v89, v89, v82
	ds_read_b128 v[82:85], v1 offset:11264
	s_waitcnt lgkmcnt(1)
	v_mul_f32_e32 v79, v57, v79
	v_fmac_f32_e32 v79, v56, v78
	v_mul_f32_e32 v78, v41, v81
	v_fmac_f32_e32 v78, v40, v80
	v_add_f32_e32 v78, v79, v78
	s_waitcnt lgkmcnt(0)
	v_mul_f32_e32 v79, v39, v83
	v_mul_f32_e32 v80, v37, v85
	v_fmac_f32_e32 v79, v38, v82
	v_fmac_f32_e32 v80, v36, v84
	v_add_f32_e32 v78, v89, v78
	v_add_f32_e32 v79, v79, v80
	v_add_f32_e32 v78, v78, v79
	ds_bpermute_b32 v88, v68, v87
	ds_bpermute_b32 v79, v66, v78
	v_add_f32_e32 v77, v77, v86
	ds_bpermute_b32 v80, v70, v77
	s_waitcnt lgkmcnt(2)
	v_add_f32_e32 v84, v87, v88
	s_waitcnt lgkmcnt(1)
	v_add_f32_e32 v79, v78, v79
	ds_bpermute_b32 v85, v69, v84
	ds_bpermute_b32 v86, v67, v79
	s_waitcnt lgkmcnt(2)
	v_add_f32_e32 v77, v77, v80
	ds_read_b128 v[80:83], v1 offset:12288
	ds_bpermute_b32 v78, v71, v77
	s_waitcnt lgkmcnt(3)
	v_add_f32_e32 v88, v84, v85
	s_waitcnt lgkmcnt(2)
	v_add_f32_e32 v79, v79, v86
	ds_read_b128 v[84:87], v1 offset:13312
	s_waitcnt lgkmcnt(2)
	v_mul_f32_e32 v81, v65, v81
	v_fmac_f32_e32 v81, v64, v80
	v_mul_f32_e32 v80, v63, v83
	v_fmac_f32_e32 v80, v62, v82
	v_add_f32_e32 v80, v81, v80
	s_waitcnt lgkmcnt(0)
	v_mul_f32_e32 v85, v61, v85
	v_add_f32_e32 v90, 0, v80
	v_fmac_f32_e32 v85, v60, v84
	v_mul_f32_e32 v84, v59, v87
	ds_read_b128 v[80:83], v1 offset:14336
	v_fmac_f32_e32 v84, v58, v86
	v_add_f32_e32 v84, v85, v84
	v_add_f32_e32 v90, v90, v84
	ds_read_b128 v[84:87], v1 offset:15360
	s_waitcnt lgkmcnt(1)
	v_mul_f32_e32 v81, v57, v81
	v_fmac_f32_e32 v81, v56, v80
	v_mul_f32_e32 v80, v41, v83
	v_fmac_f32_e32 v80, v40, v82
	v_add_f32_e32 v80, v81, v80
	s_waitcnt lgkmcnt(0)
	v_mul_f32_e32 v85, v39, v85
	v_add_f32_e32 v90, v90, v80
	v_fmac_f32_e32 v85, v38, v84
	v_mul_f32_e32 v84, v37, v87
	ds_read_b128 v[80:83], v1 offset:16384
	v_fmac_f32_e32 v84, v36, v86
	v_add_f32_e32 v84, v85, v84
	v_add_f32_e32 v90, v90, v84
	ds_read_b128 v[84:87], v1 offset:17408
	s_waitcnt lgkmcnt(1)
	v_mul_f32_e32 v81, v65, v81
	v_fmac_f32_e32 v81, v64, v80
	v_mul_f32_e32 v80, v63, v83
	v_fmac_f32_e32 v80, v62, v82
	v_add_f32_e32 v80, v81, v80
	s_waitcnt lgkmcnt(0)
	v_mul_f32_e32 v85, v61, v85
	v_add_f32_e32 v92, 0, v80
	v_fmac_f32_e32 v85, v60, v84
	v_mul_f32_e32 v84, v59, v87
	ds_read_b128 v[80:83], v1 offset:18432
	v_fmac_f32_e32 v84, v58, v86
	v_add_f32_e32 v84, v85, v84
	v_add_f32_e32 v92, v92, v84
	ds_read_b128 v[84:87], v1 offset:19456
	s_waitcnt lgkmcnt(1)
	v_mul_f32_e32 v81, v57, v81
	v_fmac_f32_e32 v81, v56, v80
	v_mul_f32_e32 v80, v41, v83
	ds_bpermute_b32 v91, v66, v90
	v_fmac_f32_e32 v80, v40, v82
	v_add_f32_e32 v80, v81, v80
	s_waitcnt lgkmcnt(1)
	v_mul_f32_e32 v81, v39, v85
	v_mul_f32_e32 v82, v37, v87
	v_fmac_f32_e32 v81, v38, v84
	v_fmac_f32_e32 v82, v36, v86
	v_add_f32_e32 v80, v92, v80
	v_add_f32_e32 v81, v81, v82
	v_add_f32_e32 v80, v80, v81
	ds_bpermute_b32 v81, v66, v80
	s_waitcnt lgkmcnt(1)
	v_add_f32_e32 v83, v90, v91
	ds_bpermute_b32 v84, v67, v83
	ds_bpermute_b32 v89, v68, v79
	ds_bpermute_b32 v82, v70, v88
	s_waitcnt lgkmcnt(3)
	v_add_f32_e32 v80, v80, v81
	ds_bpermute_b32 v81, v67, v80
	s_waitcnt lgkmcnt(3)
	v_add_f32_e32 v83, v83, v84
	ds_bpermute_b32 v84, v68, v83
	s_waitcnt lgkmcnt(3)
	v_add_f32_e32 v85, v79, v89
	ds_bpermute_b32 v86, v69, v85
	s_waitcnt lgkmcnt(2)
	v_add_f32_e32 v80, v80, v81
	ds_bpermute_b32 v81, v68, v80
	s_waitcnt lgkmcnt(2)
	v_add_f32_e32 v83, v83, v84
	ds_bpermute_b32 v84, v69, v83
	s_waitcnt lgkmcnt(2)
	v_add_f32_e32 v85, v85, v86
	ds_bpermute_b32 v86, v70, v85
	s_waitcnt lgkmcnt(2)
	v_add_f32_e32 v81, v80, v81
	ds_bpermute_b32 v87, v69, v81
	s_waitcnt lgkmcnt(2)
	v_add_f32_e32 v84, v83, v84
	v_add_f32_e32 v79, v88, v82
	ds_bpermute_b32 v88, v70, v84
	s_waitcnt lgkmcnt(2)
	v_add_f32_e32 v80, v85, v86
	s_waitcnt lgkmcnt(1)
	v_add_f32_e32 v85, v81, v87
	ds_bpermute_b32 v87, v70, v85
	ds_read_b128 v[92:95], v1 offset:21504
	s_waitcnt lgkmcnt(2)
	v_add_f32_e32 v81, v84, v88
	ds_read_b128 v[88:91], v1 offset:20480
	ds_bpermute_b32 v82, v71, v79
	s_waitcnt lgkmcnt(3)
	v_add_f32_e32 v84, v85, v87
	s_waitcnt lgkmcnt(2)
	v_mul_f32_e32 v93, v61, v93
	v_fmac_f32_e32 v93, v60, v92
	s_waitcnt lgkmcnt(1)
	v_mul_f32_e32 v87, v65, v89
	v_fmac_f32_e32 v87, v64, v88
	v_mul_f32_e32 v88, v63, v91
	v_fmac_f32_e32 v88, v62, v90
	v_mul_f32_e32 v92, v59, v95
	v_add_f32_e32 v87, v87, v88
	ds_read_b128 v[88:91], v1 offset:22528
	v_fmac_f32_e32 v92, v58, v94
	v_add_f32_e32 v87, 0, v87
	v_add_f32_e32 v92, v93, v92
	v_add_f32_e32 v87, v87, v92
	ds_read_b128 v[92:95], v1 offset:23552
	s_waitcnt lgkmcnt(1)
	v_mul_f32_e32 v89, v57, v89
	v_fmac_f32_e32 v89, v56, v88
	v_mul_f32_e32 v88, v41, v91
	v_fmac_f32_e32 v88, v40, v90
	s_waitcnt lgkmcnt(0)
	v_mul_f32_e32 v93, v39, v93
	v_add_f32_e32 v88, v89, v88
	v_fmac_f32_e32 v93, v38, v92
	v_mul_f32_e32 v92, v37, v95
	v_add_f32_e32 v87, v87, v88
	v_fmac_f32_e32 v92, v36, v94
	ds_read_b128 v[88:91], v1 offset:24576
	v_add_f32_e32 v92, v93, v92
	v_add_f32_e32 v87, v87, v92
	ds_read_b128 v[92:95], v1 offset:25600
	ds_bpermute_b32 v96, v66, v87
	s_waitcnt lgkmcnt(2)
	v_mul_f32_e32 v89, v65, v89
	v_fmac_f32_e32 v89, v64, v88
	v_mul_f32_e32 v88, v63, v91
	v_fmac_f32_e32 v88, v62, v90
	s_waitcnt lgkmcnt(1)
	v_mul_f32_e32 v93, v61, v93
	v_add_f32_e32 v88, v89, v88
	v_fmac_f32_e32 v93, v60, v92
	v_mul_f32_e32 v92, v59, v95
	v_add_f32_e32 v97, 0, v88
	ds_read_b128 v[88:91], v1 offset:26624
	v_fmac_f32_e32 v92, v58, v94
	v_add_f32_e32 v92, v93, v92
	v_add_f32_e32 v97, v97, v92
	ds_read_b128 v[92:95], v1 offset:27648
	s_waitcnt lgkmcnt(1)
	v_mul_f32_e32 v89, v57, v89
	v_fmac_f32_e32 v89, v56, v88
	v_mul_f32_e32 v88, v41, v91
	v_fmac_f32_e32 v88, v40, v90
	s_waitcnt lgkmcnt(0)
	v_mul_f32_e32 v93, v39, v93
	v_add_f32_e32 v88, v89, v88
	v_fmac_f32_e32 v93, v38, v92
	v_mul_f32_e32 v92, v37, v95
	v_add_f32_e32 v97, v97, v88
	v_fmac_f32_e32 v92, v36, v94
	ds_read_b128 v[88:91], v1 offset:28672
	v_add_f32_e32 v92, v93, v92
	v_add_f32_e32 v97, v97, v92
	ds_read_b128 v[92:95], v1 offset:29696
	ds_bpermute_b32 v98, v66, v97
	s_waitcnt lgkmcnt(2)
	v_mul_f32_e32 v65, v65, v89
	v_mul_f32_e32 v63, v63, v91
	v_fmac_f32_e32 v65, v64, v88
	v_fmac_f32_e32 v63, v62, v90
	v_add_f32_e32 v62, v65, v63
	s_waitcnt lgkmcnt(1)
	v_mul_f32_e32 v65, v61, v93
	v_add_f32_e32 v64, 0, v62
	v_fmac_f32_e32 v65, v60, v92
	ds_read_b128 v[60:63], v1 offset:30720
	ds_read_b128 v[88:91], v1 offset:31744
	v_mul_f32_e32 v59, v59, v95
	v_fmac_f32_e32 v59, v58, v94
	v_add_f32_e32 v58, v65, v59
	s_waitcnt lgkmcnt(1)
	v_mul_f32_e32 v57, v57, v61
	v_mul_f32_e32 v41, v41, v63
	v_fmac_f32_e32 v57, v56, v60
	v_fmac_f32_e32 v41, v40, v62
	s_waitcnt lgkmcnt(0)
	v_mul_f32_e32 v39, v39, v89
	v_mul_f32_e32 v37, v37, v91
	v_add_f32_e32 v58, v64, v58
	v_add_f32_e32 v40, v57, v41
	v_fmac_f32_e32 v39, v38, v88
	v_fmac_f32_e32 v37, v36, v90
	v_add_f32_e32 v40, v58, v40
	v_add_f32_e32 v36, v39, v37
	v_add_f32_e32 v36, v40, v36
	ds_bpermute_b32 v37, v66, v36
	v_add_f32_e32 v38, v87, v96
	v_add_f32_e32 v40, v97, v98
	ds_bpermute_b32 v39, v67, v38
	ds_bpermute_b32 v41, v67, v40
	s_waitcnt lgkmcnt(2)
	v_add_f32_e32 v36, v36, v37
	ds_bpermute_b32 v37, v67, v36
	ds_bpermute_b32 v83, v71, v80
	s_waitcnt lgkmcnt(3)
	v_add_f32_e32 v38, v38, v39
	s_waitcnt lgkmcnt(2)
	v_add_f32_e32 v40, v40, v41
	ds_bpermute_b32 v39, v68, v38
	s_waitcnt lgkmcnt(2)
	v_add_f32_e32 v36, v36, v37
	ds_bpermute_b32 v41, v68, v40
	ds_bpermute_b32 v37, v68, v36
	ds_bpermute_b32 v86, v71, v81
	s_waitcnt lgkmcnt(3)
	v_add_f32_e32 v38, v38, v39
	ds_bpermute_b32 v39, v69, v38
	s_waitcnt lgkmcnt(3)
	v_add_f32_e32 v40, v40, v41
	s_waitcnt lgkmcnt(2)
	v_add_f32_e32 v36, v36, v37
	ds_bpermute_b32 v41, v69, v40
	ds_bpermute_b32 v37, v69, v36
	s_waitcnt lgkmcnt(2)
	v_add_f32_e32 v38, v38, v39
	ds_bpermute_b32 v39, v70, v38
	ds_bpermute_b32 v85, v71, v84
	s_waitcnt lgkmcnt(3)
	v_add_f32_e32 v56, v40, v41
	s_waitcnt lgkmcnt(2)
	v_add_f32_e32 v36, v36, v37
	ds_bpermute_b32 v57, v70, v56
	ds_bpermute_b32 v37, v70, v36
	s_waitcnt lgkmcnt(3)
	v_add_f32_e32 v40, v38, v39
	ds_bpermute_b32 v41, v71, v40
	s_waitcnt lgkmcnt(2)
	v_add_f32_e32 v38, v56, v57
	s_waitcnt lgkmcnt(1)
	v_add_f32_e32 v36, v36, v37
	ds_bpermute_b32 v39, v71, v38
	ds_bpermute_b32 v37, v71, v36
	s_and_saveexec_b64 s[26:27], s[68:69]
	s_waitcnt vmcnt(4)
	s_cbranch_execz .LBB0_28
	v_lshl_add_u64 v[34:35], s[74:75], 0, v[52:53]
	v_add_f32_e32 v55, v77, v78
	v_add_co_u32_e32 v34, vcc, 0x26a8000, v34
	s_nop 0
	v_addc_co_u32_e32 v35, vcc, 0, v35, vcc
	s_waitcnt lgkmcnt(2)
	v_add_f32_e32 v40, v40, v41
	s_waitcnt lgkmcnt(1)
	v_add_f32_e32 v38, v38, v39
	s_waitcnt lgkmcnt(0)
	v_add_f32_e32 v36, v36, v37
	v_add_f32_e32 v56, v79, v82
	v_add_f32_e32 v57, v80, v83
	v_add_f32_e32 v58, v81, v86
	v_cndmask_b32_e64 v55, v55, v56, s[18:19]
	v_cndmask_b32_e64 v55, v55, v57, s[20:21]
	v_cndmask_b32_e64 v55, v55, v58, s[22:23]
	v_add_f32_e32 v54, v110, v55
	v_add_co_u32_e32 v34, vcc, v112, v34
	s_nop 1
	v_addc_co_u32_e32 v35, vcc, 0, v35, vcc
	global_store_dword v[34:35], v54, off
	v_add_f32_e32 v55, v84, v85
	v_cndmask_b32_e64 v55, v55, v40, s[18:19]
	v_cndmask_b32_e64 v55, v55, v38, s[20:21]
	v_cndmask_b32_e64 v55, v55, v36, s[22:23]
	v_add_f32_e32 v54, v111, v55
	s_and_b64 vcc, exec, s[4:5]
	s_cbranch_scc0 .Lp0_fnow
	v_mov_b32_e32 v113, v54
	v_mov_b32_e32 v114, v34
	v_mov_b32_e32 v115, v35
	s_branch .LBB0_28

.LBB0_28:
	s_or_b64 exec, exec, s[26:27]
	s_and_saveexec_b64 s[26:27], s[4:5]
	s_cbranch_execz .LBB0_25
	v_pk_mul_f32 v[34:35], v[32:33], v[32:33]
	s_waitcnt lgkmcnt(0)
	v_pk_mul_f32 v[36:37], v[30:31], v[30:31]
	s_nop 0
	v_pk_mov_b32 v[38:39], v[36:37], v[34:35] op_sel:[1,0]
	v_mov_b32_e32 v37, v35
	v_pk_add_f32 v[34:35], v[38:39], v[36:37]
	v_pk_mul_f32 v[36:37], v[28:29], v[28:29]
	v_pk_mul_f32 v[38:39], v[26:27], v[26:27]
	v_pk_add_f32 v[34:35], v[34:35], v[34:35] op_sel:[0,1] op_sel_hi:[1,0]
	v_pk_mov_b32 v[40:41], v[38:39], v[36:37] op_sel:[1,0]
	v_mov_b32_e32 v39, v37
	v_pk_add_f32 v[36:37], v[40:41], v[38:39]
	v_mul_f32_e32 v38, v18, v18
	v_mul_f32_e32 v39, v19, v19
	v_pk_add_f32 v[36:37], v[36:37], v[36:37] op_sel:[0,1] op_sel_hi:[1,0]
	v_mov_b32_e32 v35, v38
	v_mov_b32_e32 v37, v39
	v_pk_add_f32 v[34:35], v[34:35], v[36:37]
	v_mul_f32_e32 v36, v23, v23
	v_mul_f32_e32 v38, v25, v25
	v_mul_f32_e32 v40, v20, v20
	v_mul_f32_e32 v41, v21, v21
	v_pk_fma_f32 v[36:37], v[22:23], v[22:23], v[36:37] op_sel_hi:[1,1,0]
	v_pk_fma_f32 v[38:39], v[24:25], v[24:25], v[38:39] op_sel_hi:[1,1,0]
	v_mov_b32_e32 v37, v40
	v_mov_b32_e32 v39, v41
	v_pk_add_f32 v[36:37], v[36:37], v[38:39]
	s_nop 0
	v_pk_add_f32 v[34:35], v[34:35], v[36:37]
	v_lshl_add_u64 v[36:37], s[74:75], 0, v[48:49]
	v_add_f32_e32 v34, v34, v35
	ds_bpermute_b32 v35, v66, v34
	s_waitcnt lgkmcnt(0)
	v_add_f32_e32 v34, v34, v35
	ds_bpermute_b32 v35, v67, v34
	s_waitcnt lgkmcnt(0)
	v_add_f32_e32 v34, v34, v35
	ds_bpermute_b32 v35, v68, v34
	s_waitcnt lgkmcnt(0)
	v_add_f32_e32 v34, v34, v35
	ds_bpermute_b32 v35, v69, v34
	s_waitcnt lgkmcnt(0)
	v_add_f32_e32 v34, v34, v35
	ds_bpermute_b32 v35, v70, v34
	s_waitcnt lgkmcnt(0)
	v_add_f32_e32 v34, v34, v35
	ds_bpermute_b32 v35, v71, v34
	s_waitcnt lgkmcnt(0)
	v_add_f32_e32 v34, v34, v35
	v_fmamk_f32 v34, v34, 0x3a800000, v74
	v_mul_f32_e32 v35, 0x4b800000, v34
	v_cmp_gt_f32_e32 vcc, s28, v34
	s_nop 1
	v_cndmask_b32_e32 v34, v34, v35, vcc
	v_rsq_f32_e32 v34, v34
	s_nop 0
	v_mul_f32_e32 v35, 0x45800000, v34
	v_cndmask_b32_e32 v38, v34, v35, vcc
	v_pk_mul_f32 v[30:31], v[30:31], v[38:39] op_sel_hi:[1,0]
	v_pk_mul_f32 v[32:33], v[32:33], v[38:39] op_sel_hi:[1,0]
	v_pk_mul_f32 v[34:35], v[2:3], v[30:31]
	v_add_co_u32_e32 v30, vcc, s29, v36
	v_pk_mul_f32 v[32:33], v[4:5], v[32:33]
	s_nop 0
	v_addc_co_u32_e32 v31, vcc, 0, v37, vcc
	v_pk_mul_f32 v[36:37], v[26:27], v[38:39] op_sel_hi:[1,0]
	v_pk_mul_f32 v[26:27], v[28:29], v[38:39] op_sel_hi:[1,0]
	v_cvt_pk_bf16_f32 v40, v34, v35
	v_cvt_pk_bf16_f32 v41, v32, v33
	global_store_dwordx2 v[30:31], v[40:41], off
	v_pk_mul_f32 v[26:27], v[8:9], v[26:27]
	v_pk_mul_f32 v[28:29], v[6:7], v[36:37]
	v_pk_mul_f32 v[18:19], v[18:19], v[38:39] op_sel_hi:[1,0]
	v_cvt_pk_bf16_f32 v36, v28, v29
	v_cvt_pk_bf16_f32 v37, v26, v27
	global_store_dwordx2 v[30:31], v[36:37], off offset:512
	v_pk_mul_f32 v[36:37], v[22:23], v[38:39] op_sel_hi:[1,0]
	v_pk_mul_f32 v[22:23], v[24:25], v[38:39] op_sel_hi:[1,0]
	v_pk_mul_f32 v[24:25], v[10:11], v[36:37]
	v_pk_mul_f32 v[22:23], v[12:13], v[22:23]
	v_cvt_pk_bf16_f32 v36, v24, v25
	v_pk_mul_f32 v[20:21], v[20:21], v[38:39] op_sel_hi:[1,0]
	v_cvt_pk_bf16_f32 v37, v22, v23
	global_store_dwordx2 v[30:31], v[36:37], off offset:1024
	v_pk_mul_f32 v[20:21], v[16:17], v[20:21]
	v_pk_mul_f32 v[36:37], v[14:15], v[18:19]
	s_nop 0
	v_cvt_pk_bf16_f32 v18, v36, v37
	v_cvt_pk_bf16_f32 v19, v20, v21
	ds_read_b128 v[38:41], v1
	ds_read_b128 v[54:57], v1 offset:1024
	global_store_dwordx2 v[30:31], v[18:19], off offset:1536
	ds_read_b128 v[78:81], v1 offset:21504
	s_waitcnt lgkmcnt(2)
	v_mul_f32_e32 v39, v35, v39
	v_fmac_f32_e32 v39, v34, v38
	v_mul_f32_e32 v38, v33, v41
	v_fmac_f32_e32 v38, v32, v40
	v_add_f32_e32 v38, v39, v38
	s_waitcnt lgkmcnt(1)
	v_mul_f32_e32 v55, v29, v55
	v_add_f32_e32 v58, 0, v38
	v_fmac_f32_e32 v55, v28, v54
	v_mul_f32_e32 v54, v27, v57
	ds_read_b128 v[38:41], v1 offset:2048
	v_fmac_f32_e32 v54, v26, v56
	v_add_f32_e32 v54, v55, v54
	v_add_f32_e32 v58, v58, v54
	ds_read_b128 v[54:57], v1 offset:3072
	s_waitcnt lgkmcnt(1)
	v_mul_f32_e32 v39, v25, v39
	v_fmac_f32_e32 v39, v24, v38
	v_mul_f32_e32 v38, v23, v41
	v_fmac_f32_e32 v38, v22, v40
	v_add_f32_e32 v38, v39, v38
	s_waitcnt lgkmcnt(0)
	v_mul_f32_e32 v39, v37, v55
	v_mul_f32_e32 v40, v21, v57
	v_fmac_f32_e32 v39, v36, v54
	v_fmac_f32_e32 v40, v20, v56
	v_add_f32_e32 v38, v58, v38
	v_add_f32_e32 v39, v39, v40
	v_add_f32_e32 v54, v38, v39
	ds_bpermute_b32 v55, v66, v54
	ds_read_b128 v[38:41], v1 offset:4096
	v_mul_f32_e32 v77, v27, v81
	v_fmac_f32_e32 v77, v26, v80
	s_waitcnt lgkmcnt(1)
	v_add_f32_e32 v58, v54, v55
	ds_read_b128 v[54:57], v1 offset:5120
	s_waitcnt lgkmcnt(1)
	v_mul_f32_e32 v39, v35, v39
	v_fmac_f32_e32 v39, v34, v38
	v_mul_f32_e32 v38, v33, v41
	v_fmac_f32_e32 v38, v32, v40
	v_add_f32_e32 v38, v39, v38
	s_waitcnt lgkmcnt(0)
	v_mul_f32_e32 v55, v29, v55
	v_add_f32_e32 v60, 0, v38
	v_fmac_f32_e32 v55, v28, v54
	v_mul_f32_e32 v54, v27, v57
	ds_read_b128 v[38:41], v1 offset:6144
	v_fmac_f32_e32 v54, v26, v56
	v_add_f32_e32 v54, v55, v54
	v_add_f32_e32 v60, v60, v54
	ds_read_b128 v[54:57], v1 offset:7168
	s_waitcnt lgkmcnt(1)
	v_mul_f32_e32 v39, v25, v39
	v_fmac_f32_e32 v39, v24, v38
	v_mul_f32_e32 v38, v23, v41
	v_fmac_f32_e32 v38, v22, v40
	v_add_f32_e32 v38, v39, v38
	s_waitcnt lgkmcnt(0)
	v_mul_f32_e32 v39, v37, v55
	v_mul_f32_e32 v40, v21, v57
	ds_bpermute_b32 v59, v67, v58
	v_fmac_f32_e32 v39, v36, v54
	v_fmac_f32_e32 v40, v20, v56
	v_add_f32_e32 v38, v60, v38
	v_add_f32_e32 v39, v39, v40
	v_add_f32_e32 v38, v38, v39
	ds_bpermute_b32 v39, v66, v38
	s_waitcnt lgkmcnt(1)
	v_add_f32_e32 v40, v58, v59
	ds_bpermute_b32 v41, v68, v40
	s_waitcnt lgkmcnt(1)
	v_add_f32_e32 v54, v38, v39
	ds_bpermute_b32 v55, v67, v54
	s_waitcnt lgkmcnt(1)
	v_add_f32_e32 v58, v40, v41
	ds_read_b128 v[38:41], v1 offset:8192
	ds_bpermute_b32 v59, v69, v58
	s_waitcnt lgkmcnt(2)
	v_add_f32_e32 v60, v54, v55
	ds_read_b128 v[54:57], v1 offset:9216
	s_waitcnt lgkmcnt(2)
	v_mul_f32_e32 v39, v35, v39
	v_fmac_f32_e32 v39, v34, v38
	v_mul_f32_e32 v38, v33, v41
	v_fmac_f32_e32 v38, v32, v40
	v_add_f32_e32 v38, v39, v38
	s_waitcnt lgkmcnt(0)
	v_mul_f32_e32 v55, v29, v55
	v_add_f32_e32 v62, 0, v38
	v_fmac_f32_e32 v55, v28, v54
	v_mul_f32_e32 v54, v27, v57
	ds_read_b128 v[38:41], v1 offset:10240
	v_fmac_f32_e32 v54, v26, v56
	v_add_f32_e32 v54, v55, v54
	v_add_f32_e32 v62, v62, v54
	ds_read_b128 v[54:57], v1 offset:11264
	s_waitcnt lgkmcnt(1)
	v_mul_f32_e32 v39, v25, v39
	v_fmac_f32_e32 v39, v24, v38
	v_mul_f32_e32 v38, v23, v41
	v_fmac_f32_e32 v38, v22, v40
	v_add_f32_e32 v38, v39, v38
	s_waitcnt lgkmcnt(0)
	v_mul_f32_e32 v39, v37, v55
	v_mul_f32_e32 v40, v21, v57
	v_fmac_f32_e32 v39, v36, v54
	v_fmac_f32_e32 v40, v20, v56
	v_add_f32_e32 v38, v62, v38
	v_add_f32_e32 v39, v39, v40
	v_add_f32_e32 v38, v38, v39
	ds_bpermute_b32 v61, v68, v60
	ds_bpermute_b32 v39, v66, v38
	v_add_f32_e32 v40, v58, v59
	ds_bpermute_b32 v41, v70, v40
	ds_read_b128 v[54:57], v1 offset:12288
	s_waitcnt lgkmcnt(3)
	v_add_f32_e32 v58, v60, v61
	s_waitcnt lgkmcnt(2)
	v_add_f32_e32 v60, v38, v39
	ds_bpermute_b32 v59, v69, v58
	ds_bpermute_b32 v61, v67, v60
	s_waitcnt lgkmcnt(3)
	v_add_f32_e32 v38, v40, v41
	ds_bpermute_b32 v39, v71, v38
	s_waitcnt lgkmcnt(2)
	v_add_f32_e32 v40, v58, v59
	s_waitcnt lgkmcnt(1)
	v_add_f32_e32 v41, v60, v61
	ds_read_b128 v[58:61], v1 offset:13312
	v_mul_f32_e32 v55, v35, v55
	v_fmac_f32_e32 v55, v34, v54
	v_mul_f32_e32 v54, v33, v57
	v_fmac_f32_e32 v54, v32, v56
	v_add_f32_e32 v54, v55, v54
	s_waitcnt lgkmcnt(0)
	v_mul_f32_e32 v59, v29, v59
	v_add_f32_e32 v63, 0, v54
	v_fmac_f32_e32 v59, v28, v58
	v_mul_f32_e32 v58, v27, v61
	ds_read_b128 v[54:57], v1 offset:14336
	v_fmac_f32_e32 v58, v26, v60
	v_add_f32_e32 v58, v59, v58
	v_add_f32_e32 v63, v63, v58
	ds_read_b128 v[58:61], v1 offset:15360
	s_waitcnt lgkmcnt(1)
	v_mul_f32_e32 v55, v25, v55
	v_fmac_f32_e32 v55, v24, v54
	v_mul_f32_e32 v54, v23, v57
	v_fmac_f32_e32 v54, v22, v56
	v_add_f32_e32 v54, v55, v54
	s_waitcnt lgkmcnt(0)
	v_mul_f32_e32 v59, v37, v59
	v_add_f32_e32 v63, v63, v54
	v_fmac_f32_e32 v59, v36, v58
	v_mul_f32_e32 v58, v21, v61
	ds_read_b128 v[54:57], v1 offset:16384
	v_fmac_f32_e32 v58, v20, v60
	v_add_f32_e32 v58, v59, v58
	v_add_f32_e32 v63, v63, v58
	ds_read_b128 v[58:61], v1 offset:17408
	s_waitcnt lgkmcnt(1)
	v_mul_f32_e32 v55, v35, v55
	v_fmac_f32_e32 v55, v34, v54
	v_mul_f32_e32 v54, v33, v57
	v_fmac_f32_e32 v54, v32, v56
	v_add_f32_e32 v54, v55, v54
	s_waitcnt lgkmcnt(0)
	v_mul_f32_e32 v59, v29, v59
	v_add_f32_e32 v65, 0, v54
	v_fmac_f32_e32 v59, v28, v58
	v_mul_f32_e32 v58, v27, v61
	ds_read_b128 v[54:57], v1 offset:18432
	v_fmac_f32_e32 v58, v26, v60
	v_add_f32_e32 v58, v59, v58
	v_add_f32_e32 v65, v65, v58
	ds_read_b128 v[58:61], v1 offset:19456
	s_waitcnt lgkmcnt(1)
	v_mul_f32_e32 v55, v25, v55
	v_fmac_f32_e32 v55, v24, v54
	v_mul_f32_e32 v54, v23, v57
	v_fmac_f32_e32 v54, v22, v56
	v_add_f32_e32 v54, v55, v54
	s_waitcnt lgkmcnt(0)
	v_mul_f32_e32 v55, v37, v59
	v_mul_f32_e32 v56, v21, v61
	v_fmac_f32_e32 v55, v36, v58
	v_fmac_f32_e32 v56, v20, v60
	v_add_f32_e32 v54, v65, v54
	v_add_f32_e32 v55, v55, v56
	v_add_f32_e32 v54, v54, v55
	ds_bpermute_b32 v64, v66, v63
	ds_bpermute_b32 v55, v66, v54
	ds_bpermute_b32 v62, v68, v41
	ds_bpermute_b32 v56, v70, v40
	s_waitcnt lgkmcnt(3)
	v_add_f32_e32 v57, v63, v64
	s_waitcnt lgkmcnt(2)
	v_add_f32_e32 v54, v54, v55
	ds_bpermute_b32 v58, v67, v57
	ds_bpermute_b32 v55, v67, v54
	s_waitcnt lgkmcnt(3)
	v_add_f32_e32 v41, v41, v62
	ds_bpermute_b32 v59, v69, v41
	s_waitcnt lgkmcnt(3)
	v_add_f32_e32 v40, v40, v56
	s_waitcnt lgkmcnt(2)
	v_add_f32_e32 v57, v57, v58
	s_waitcnt lgkmcnt(1)
	v_add_f32_e32 v54, v54, v55
	ds_bpermute_b32 v58, v68, v57
	ds_bpermute_b32 v55, v68, v54
	s_waitcnt lgkmcnt(2)
	v_add_f32_e32 v41, v41, v59
	ds_read_b128 v[60:63], v1 offset:20480
	s_waitcnt lgkmcnt(2)
	v_add_f32_e32 v56, v57, v58
	s_waitcnt lgkmcnt(1)
	v_add_f32_e32 v54, v54, v55
	ds_bpermute_b32 v57, v69, v56
	ds_bpermute_b32 v59, v69, v54
	s_waitcnt lgkmcnt(2)
	v_mul_f32_e32 v61, v35, v61
	v_fmac_f32_e32 v61, v34, v60
	v_mul_f32_e32 v60, v33, v63
	s_waitcnt lgkmcnt(1)
	v_add_f32_e32 v56, v56, v57
	s_waitcnt lgkmcnt(0)
	v_add_f32_e32 v64, v54, v59
	ds_bpermute_b32 v57, v70, v56
	ds_bpermute_b32 v65, v70, v64
	v_fmac_f32_e32 v60, v32, v62
	v_add_f32_e32 v60, v61, v60
	ds_bpermute_b32 v58, v70, v41
	s_waitcnt lgkmcnt(2)
	v_add_f32_e32 v54, v56, v57
	s_waitcnt lgkmcnt(1)
	v_add_f32_e32 v56, v64, v65
	v_add_f32_e32 v64, 0, v60
	ds_read_b128 v[60:63], v1 offset:22528
	v_mul_f32_e32 v65, v29, v79
	v_fmac_f32_e32 v65, v28, v78
	ds_read_b128 v[78:81], v1 offset:23552
	v_add_f32_e32 v65, v65, v77
	s_waitcnt lgkmcnt(1)
	v_mul_f32_e32 v61, v25, v61
	v_fmac_f32_e32 v61, v24, v60
	v_mul_f32_e32 v60, v23, v63
	v_fmac_f32_e32 v60, v22, v62
	v_add_f32_e32 v64, v64, v65
	v_add_f32_e32 v60, v61, v60
	v_add_f32_e32 v64, v64, v60
	ds_read_b128 v[60:63], v1 offset:24576
	s_waitcnt lgkmcnt(1)
	v_mul_f32_e32 v65, v37, v79
	v_mul_f32_e32 v77, v21, v81
	v_fmac_f32_e32 v65, v36, v78
	v_fmac_f32_e32 v77, v20, v80
	ds_read_b128 v[78:81], v1 offset:25600
	s_waitcnt lgkmcnt(1)
	v_mul_f32_e32 v61, v35, v61
	v_fmac_f32_e32 v61, v34, v60
	v_mul_f32_e32 v60, v33, v63
	v_fmac_f32_e32 v60, v32, v62
	s_waitcnt lgkmcnt(0)
	v_mul_f32_e32 v79, v29, v79
	v_add_f32_e32 v60, v61, v60
	v_fmac_f32_e32 v79, v28, v78
	v_mul_f32_e32 v78, v27, v81
	v_add_f32_e32 v65, v65, v77
	v_add_f32_e32 v77, 0, v60
	ds_read_b128 v[60:63], v1 offset:26624
	v_fmac_f32_e32 v78, v26, v80
	v_add_f32_e32 v78, v79, v78
	v_add_f32_e32 v77, v77, v78
	ds_read_b128 v[78:81], v1 offset:27648
	s_waitcnt lgkmcnt(1)
	v_mul_f32_e32 v61, v25, v61
	v_fmac_f32_e32 v61, v24, v60
	v_mul_f32_e32 v60, v23, v63
	v_fmac_f32_e32 v60, v22, v62
	s_waitcnt lgkmcnt(0)
	v_mul_f32_e32 v79, v37, v79
	v_add_f32_e32 v60, v61, v60
	v_fmac_f32_e32 v79, v36, v78
	v_mul_f32_e32 v78, v21, v81
	v_add_f32_e32 v77, v77, v60
	v_fmac_f32_e32 v78, v20, v80
	ds_read_b128 v[60:63], v1 offset:28672
	v_add_f32_e32 v78, v79, v78
	v_add_f32_e32 v77, v77, v78
	ds_read_b128 v[78:81], v1 offset:29696
	v_add_f32_e32 v64, v64, v65
	s_waitcnt lgkmcnt(1)
	v_mul_f32_e32 v35, v35, v61
	v_mul_f32_e32 v33, v33, v63
	v_fmac_f32_e32 v35, v34, v60
	v_fmac_f32_e32 v33, v32, v62
	v_add_f32_e32 v32, v35, v33
	s_waitcnt lgkmcnt(0)
	v_mul_f32_e32 v29, v29, v79
	v_mul_f32_e32 v27, v27, v81
	v_add_f32_e32 v60, 0, v32
	v_fmac_f32_e32 v29, v28, v78
	ds_read_b128 v[32:35], v1 offset:30720
	v_fmac_f32_e32 v27, v26, v80
	v_add_f32_e32 v26, v29, v27
	v_add_f32_e32 v60, v60, v26
	ds_read_b128 v[26:29], v1 offset:31744
	s_waitcnt lgkmcnt(1)
	v_mul_f32_e32 v25, v25, v33
	v_mul_f32_e32 v23, v23, v35
	v_fmac_f32_e32 v25, v24, v32
	v_fmac_f32_e32 v23, v22, v34
	v_add_f32_e32 v22, v25, v23
	s_waitcnt lgkmcnt(0)
	v_mul_f32_e32 v23, v37, v27
	v_mul_f32_e32 v21, v21, v29
	v_fmac_f32_e32 v23, v36, v26
	v_fmac_f32_e32 v21, v20, v28
	v_add_f32_e32 v22, v60, v22
	v_add_f32_e32 v20, v23, v21
	v_add_f32_e32 v20, v22, v20
	ds_bpermute_b32 v65, v66, v64
	ds_bpermute_b32 v82, v66, v77
	ds_bpermute_b32 v21, v66, v20
	v_add_f32_e32 v41, v41, v58
	ds_bpermute_b32 v55, v71, v40
	s_waitcnt lgkmcnt(3)
	v_add_f32_e32 v22, v64, v65
	s_waitcnt lgkmcnt(2)
	v_add_f32_e32 v24, v77, v82
	s_waitcnt lgkmcnt(1)
	v_add_f32_e32 v20, v20, v21
	ds_bpermute_b32 v23, v67, v22
	ds_bpermute_b32 v25, v67, v24
	ds_bpermute_b32 v21, v67, v20
	ds_bpermute_b32 v58, v71, v41
	ds_bpermute_b32 v59, v71, v54
	s_waitcnt lgkmcnt(4)
	v_add_f32_e32 v22, v22, v23
	s_waitcnt lgkmcnt(3)
	v_add_f32_e32 v24, v24, v25
	s_waitcnt lgkmcnt(2)
	v_add_f32_e32 v20, v20, v21
	ds_bpermute_b32 v23, v68, v22
	ds_bpermute_b32 v25, v68, v24
	ds_bpermute_b32 v21, v68, v20
	ds_bpermute_b32 v57, v71, v56
	s_waitcnt lgkmcnt(3)
	v_add_f32_e32 v22, v22, v23
	s_waitcnt lgkmcnt(2)
	v_add_f32_e32 v24, v24, v25
	s_waitcnt lgkmcnt(1)
	v_add_f32_e32 v20, v20, v21
	ds_bpermute_b32 v23, v69, v22
	ds_bpermute_b32 v25, v69, v24
	ds_bpermute_b32 v21, v69, v20
	s_waitcnt lgkmcnt(2)
	v_add_f32_e32 v22, v22, v23
	s_waitcnt lgkmcnt(1)
	v_add_f32_e32 v26, v24, v25
	s_waitcnt lgkmcnt(0)
	v_add_f32_e32 v20, v20, v21
	ds_bpermute_b32 v23, v70, v22
	ds_bpermute_b32 v27, v70, v26
	ds_bpermute_b32 v21, v70, v20
	s_waitcnt lgkmcnt(2)
	v_add_f32_e32 v24, v22, v23
	s_waitcnt lgkmcnt(1)
	v_add_f32_e32 v22, v26, v27
	s_waitcnt lgkmcnt(0)
	v_add_f32_e32 v20, v20, v21
	ds_bpermute_b32 v25, v71, v24
	ds_bpermute_b32 v23, v71, v22
	ds_bpermute_b32 v21, v71, v20
	s_and_b64 exec, exec, s[68:69]
	s_cbranch_execz .LBB0_25
	v_lshl_add_u64 v[18:19], s[74:75], 0, v[46:47]
	v_add_f32_e32 v27, v38, v39
	v_add_co_u32_e32 v18, vcc, 0x26a8000, v18
	s_nop 0
	v_addc_co_u32_e32 v19, vcc, 0, v19, vcc
	s_waitcnt lgkmcnt(2)
	v_add_f32_e32 v24, v24, v25
	s_waitcnt lgkmcnt(1)
	v_add_f32_e32 v22, v22, v23
	s_waitcnt lgkmcnt(0)
	v_add_f32_e32 v20, v20, v21
	v_add_f32_e32 v28, v40, v55
	v_add_f32_e32 v29, v41, v58
	v_add_f32_e32 v30, v54, v59
	v_cndmask_b32_e64 v27, v27, v28, s[18:19]
	v_cndmask_b32_e64 v27, v27, v29, s[20:21]
	v_cndmask_b32_e64 v27, v27, v30, s[22:23]
	v_add_f32_e32 v26, v110, v27
	v_add_co_u32_e32 v18, vcc, v112, v18
	s_nop 1
	v_addc_co_u32_e32 v19, vcc, 0, v19, vcc
	global_store_dword v[18:19], v26, off
	v_add_f32_e32 v27, v56, v57
	v_cndmask_b32_e64 v27, v27, v24, s[18:19]
	v_cndmask_b32_e64 v27, v27, v22, s[20:21]
	v_cndmask_b32_e64 v27, v27, v20, s[22:23]
	v_add_f32_e32 v26, v111, v27
	s_mov_b64 exec, 0xff
	s_nop 4
	v_mov_b32_dpp v26, v113 row_shr:4 row_mask:0xf bank_mask:0x2
	v_mov_b32_dpp v18, v114 row_shr:4 row_mask:0xf bank_mask:0x2
	v_mov_b32_dpp v19, v115 row_shr:4 row_mask:0xf bank_mask:0x2
	v_mul_f32_e64 v27, |v26|, s30
	v_fma_f32 v28, |v26|, s30, -v27
	v_rndne_f32_e32 v29, v27
	v_fma_f32 v28, |v26|, s31, v28
	v_sub_f32_e32 v27, v27, v29
	v_add_f32_e32 v27, v27, v28
	v_cvt_i32_f32_e32 v29, v29
	v_exp_f32_e32 v27, v27
	v_cmp_ngt_f32_e64 vcc, |v26|, s34
	v_min_f32_e32 v28, 0, v26
	v_ldexp_f32 v27, v27, v29
	v_cndmask_b32_e32 v27, 0, v27, vcc
	v_cmp_nlt_f32_e64 vcc, |v26|, s35
	s_nop 1
	v_cndmask_b32_e32 v29, v76, v27, vcc
	v_add_f32_e32 v30, 1.0, v29
	v_add_f32_e32 v31, -1.0, v30
	v_frexp_mant_f32_e32 v32, v30
	v_cvt_f64_f32_e32 v[26:27], v30
	v_sub_f32_e32 v33, v31, v30
	v_frexp_exp_i32_f64_e32 v26, v[26:27]
	v_cmp_gt_f32_e32 vcc, s65, v32
	v_sub_f32_e32 v31, v29, v31
	v_add_f32_e32 v27, 1.0, v33
	v_subbrev_co_u32_e32 v26, vcc, 0, v26, vcc
	v_add_f32_e32 v27, v31, v27
	v_sub_u32_e32 v31, 0, v26
	v_cvt_f32_i32_e32 v26, v26
	v_ldexp_f32 v30, v30, v31
	v_ldexp_f32 v27, v27, v31
	v_add_f32_e32 v31, -1.0, v30
	v_add_f32_e32 v32, 1.0, v30
	v_add_f32_e32 v33, 1.0, v31
	v_add_f32_e32 v34, -1.0, v32
	v_sub_f32_e32 v33, v30, v33
	v_sub_f32_e32 v30, v30, v34
	v_mul_f32_e32 v34, 0x3f317218, v26
	v_add_f32_e32 v33, v27, v33
	v_add_f32_e32 v27, v27, v30
	v_fma_f32 v30, v26, s66, -v34
	v_add_f32_e32 v35, v31, v33
	v_add_f32_e32 v36, v32, v27
	v_fmac_f32_e32 v30, 0xb102e308, v26
	v_sub_f32_e32 v26, v31, v35
	v_sub_f32_e32 v31, v32, v36
	v_rcp_f32_e32 v32, v36
	v_add_f32_e32 v37, v34, v30
	v_add_f32_e32 v27, v27, v31
	v_sub_f32_e32 v31, v37, v34
	v_sub_f32_e32 v30, v30, v31
	v_mul_f32_e32 v31, v35, v32
	v_add_f32_e32 v26, v33, v26
	v_mul_f32_e32 v33, v36, v31
	v_fma_f32 v34, v31, v36, -v33
	v_fmac_f32_e32 v34, v31, v27
	v_add_f32_e32 v38, v33, v34
	v_sub_f32_e32 v39, v35, v38
	v_sub_f32_e32 v33, v38, v33
	v_sub_f32_e32 v35, v35, v39
	v_sub_f32_e32 v33, v33, v34
	v_sub_f32_e32 v34, v35, v38
	v_add_f32_e32 v26, v26, v34
	v_add_f32_e32 v26, v33, v26
	v_add_f32_e32 v33, v39, v26
	v_mul_f32_e32 v34, v32, v33
	v_sub_f32_e32 v35, v39, v33
	v_mul_f32_e32 v38, v36, v34
	v_add_f32_e32 v26, v26, v35
	v_add_f32_e32 v35, v31, v34
	v_fma_f32 v36, v34, v36, -v38
	v_sub_f32_e32 v31, v35, v31
	v_fmac_f32_e32 v36, v34, v27
	v_sub_f32_e32 v27, v34, v31
	v_add_f32_e32 v31, v38, v36
	v_sub_f32_e32 v34, v31, v38
	v_sub_f32_e32 v38, v33, v31
	v_sub_f32_e32 v33, v33, v38
	v_sub_f32_e32 v31, v33, v31
	v_sub_f32_e32 v34, v34, v36
	v_add_f32_e32 v26, v26, v31
	v_add_f32_e32 v26, v34, v26
	v_add_f32_e32 v26, v38, v26
	v_mul_f32_e32 v26, v32, v26
	v_add_f32_e32 v26, v27, v26
	v_add_f32_e32 v27, v35, v26
	v_mul_f32_e32 v31, v27, v27
	v_fmamk_f32 v34, v31, 0x3e9b6dac, v75
	v_sub_f32_e32 v32, v27, v35
	v_ldexp_f32 v33, v27, 1
	v_mul_f32_e32 v27, v27, v31
	v_fmaak_f32 v31, v31, v34, 0x3f2aaada
	v_mul_f32_e32 v27, v27, v31
	v_add_f32_e32 v31, v33, v27
	v_sub_f32_e32 v26, v26, v32
	v_sub_f32_e32 v32, v31, v33
	v_ldexp_f32 v26, v26, 1
	v_sub_f32_e32 v27, v27, v32
	v_add_f32_e32 v26, v26, v27
	v_add_f32_e32 v27, v31, v26
	v_sub_f32_e32 v31, v27, v31
	v_add_f32_e32 v32, v37, v27
	v_sub_f32_e32 v26, v26, v31
	v_sub_f32_e32 v31, v32, v37
	v_sub_f32_e32 v33, v32, v31
	v_sub_f32_e32 v27, v27, v31
	v_add_f32_e32 v31, v30, v26
	v_sub_f32_e32 v33, v37, v33
	v_sub_f32_e32 v34, v31, v30
	v_add_f32_e32 v27, v27, v33
	v_sub_f32_e32 v33, v31, v34
	v_sub_f32_e32 v26, v26, v34
	v_sub_f32_e32 v30, v30, v33
	v_add_f32_e32 v27, v31, v27
	v_add_f32_e32 v26, v26, v30
	v_add_f32_e32 v30, v32, v27
	v_sub_f32_e32 v31, v30, v32
	v_sub_f32_e32 v27, v27, v31
	v_add_f32_e32 v26, v26, v27
	v_add_f32_e32 v26, v30, v26
	v_cmp_neq_f32_e32 vcc, s64, v29
	s_nop 1
	v_cndmask_b32_e32 v26, v76, v26, vcc
	v_cmp_lt_f32_e64 vcc, |v29|, s67
	s_nop 1
	v_cndmask_b32_e32 v26, v26, v29, vcc
	v_sub_f32_e32 v26, v28, v26
	global_store_dword v[18:19], v26, off offset:16
	s_branch .LBB0_25
.LBB0_31:
	s_or_b64 exec, exec, s[0:1]
	v_readlane_b32 s36, v254, 5
	v_readlane_b32 s37, v254, 6
	v_readlane_b32 s38, v254, 7
	v_readlane_b32 s39, v254, 8
	v_readlane_b32 s40, v254, 9
	v_readlane_b32 s41, v254, 10
	v_readlane_b32 s42, v254, 11
	v_readlane_b32 s43, v254, 12
	v_readlane_b32 s44, v254, 13
	v_readlane_b32 s45, v254, 14
	v_readlane_b32 s46, v254, 15
	v_readlane_b32 s47, v254, 16
	v_readlane_b32 s48, v254, 17
	v_readlane_b32 s49, v254, 18
	v_readlane_b32 s50, v254, 19
	v_readlane_b32 s51, v254, 20
	s_waitcnt vmcnt(0)
	s_waitcnt lgkmcnt(0)
	s_barrier
	s_mov_b64 s[0:1], exec
	v_readlane_b32 s2, v254, 2
	v_readlane_b32 s3, v254, 3
	s_and_b64 s[2:3], s[0:1], s[2:3]
	s_mov_b64 exec, s[2:3]
	s_cbranch_execz .LBB0_83
	s_add_i32 s2, 0, 0x21fe0
	v_mov_b32_e32 v1, s2
	s_waitcnt vmcnt(0) expcnt(0) lgkmcnt(0)
	ds_read_b32 v3, v1
	s_add_i32 s2, 0, 0x21fe4
	v_mov_b32_e32 v1, s2
	ds_read_b32 v1, v1
	s_waitcnt lgkmcnt(1)
	v_cmp_ne_u32_e32 vcc, 0, v3
	s_cbranch_vccnz .LBB0_47
	v_readlane_b32 s2, v254, 0
	v_readlane_b32 s3, v254, 1
	s_load_dwordx2 s[6:7], s[2:3], 0x4
	s_add_u32 s2, s74, 0x1000
	s_addc_u32 s3, s75, 0
	s_add_u32 s4, s74, 0x1100
	s_addc_u32 s5, s75, 0
	s_waitcnt lgkmcnt(0)
	s_mul_i32 s20, s6, s90
	s_add_u32 s6, s74, 0x1200
	s_mul_i32 s20, s20, s7
	s_addc_u32 s7, s75, 0
	s_add_u32 s8, s74, 0x1300
	s_addc_u32 s9, s75, 0
	s_mov_b32 s21, 1
	v_mov_b32_e32 v17, 0
	s_branch .LBB0_35
